# forgetting loop: the early-exit bound's LDS read (last-key cumulative gate) issued at the top of each step so its latency hides under the tile-load address arithmetic
# baseline (speedup 1.0000x reference)
; template <int TYPE>
; DI void attn_item(KargPtr p, int b, int h, int qb, unsigned char* smem) {
;     ...
;     auto compute = [&](const int kt, const int buf) __attribute__((always_inline)) {
;         const unsigned char* kb = smem + buf * BUFB; const unsigned char* vb = kb + KBYTES;
;         const int k0 = kt * 64;
;         bool need;
;         if (TYPE == 0) {
;             if (!wdone && k0 <= qw + 31) wdone = (__all(qbound + *(const float*)(vb + VBYTES) - m < -150.f) != 0);
;             need = (k0 <= qw + 31) && !wdone;
.LBB0_608:
	v_mov_b32_e32 v225, s3
	ds_read_b32 v225, v225 offset:41216
	s_add_i32 s84, s84, 3
	s_add_i32 s10, s74, 0xffffff41
	v_readlane_b32 s11, v255, 22
	s_cmp_lt_u32 s84, s11
	s_cselect_b32 s10, s10, 0
	v_add_u32_e32 v0, s10, v173
	v_ashrrev_i32_e32 v1, 31, v0
	v_lshlrev_b64 v[0:1], 10, v[0:1]
	v_lshl_add_u64 v[0:1], s[88:89], 0, v[0:1]
	v_mov_b32_e32 v155, v3
	v_lshl_add_u64 v[0:1], v[0:1], 0, v[154:155]
	global_load_dwordx4 v[108:111], v[0:1], off
	v_add_u32_e32 v0, s10, v174
	v_ashrrev_i32_e32 v1, 31, v0
	s_ashr_i32 s11, s10, 31
	v_lshlrev_b64 v[0:1], 10, v[0:1]
	s_lshl_b64 s[12:13], s[10:11], 7
	v_lshl_add_u64 v[0:1], s[88:89], 0, v[0:1]
	s_add_u32 s12, s75, s12
	v_lshl_add_u64 v[0:1], v[0:1], 0, v[154:155]
	s_addc_u32 s13, s76, s13
	global_load_dwordx4 v[112:115], v[0:1], off
	v_lshl_add_u64 v[0:1], v[132:133], 1, s[12:13]
	v_lshl_add_u64 v[0:1], v[0:1], 0, v[154:155]
	s_lshl_b64 s[10:11], s[10:11], 2
	global_load_dwordx4 v[116:119], v[0:1], off
	v_lshl_add_u64 v[0:1], v[134:135], 1, s[12:13]
	s_add_u32 s10, s77, s10
	v_lshl_add_u64 v[0:1], v[0:1], 0, v[154:155]
	s_addc_u32 s11, s96, s11
	v_mov_b32_e32 v137, v3
	global_load_dwordx4 v[120:123], v[0:1], off
	v_lshl_add_u64 v[0:1], s[10:11], 0, v[136:137]
	global_load_dword v137, v[0:1], off
	v_and_b32_e32 v0, 1, v189
	s_sub_i32 s12, s74, 63
	v_cmp_eq_u32_e64 s[10:11], 1, v0
	v_cmp_gt_i32_e32 vcc, s12, v184
	s_xor_b64 s[12:13], s[10:11], -1
	s_nor_b64 s[16:17], s[10:11], vcc
	s_or_b64 s[12:13], s[12:13], vcc
	s_and_saveexec_b64 s[14:15], s[16:17]
	s_cbranch_execz .LBB0_610
	s_mov_b32 s16, 0xc3160000
	s_waitcnt lgkmcnt(0)
	v_add_f32_e32 v0, v182, v225
	v_sub_f32_e32 v0, v0, v160
	v_cmp_gt_f32_e32 vcc, s16, v0
	s_cmp_eq_u64 vcc, exec
	s_cselect_b64 s[16:17], -1, 0
	v_cndmask_b32_e64 v189, 0, 1, s[16:17]
	s_andn2_b64 s[10:11], s[10:11], exec
	s_and_b64 s[16:17], s[16:17], exec
	s_andn2_b64 s[12:13], s[12:13], exec
	s_or_b64 s[10:11], s[10:11], s[16:17]

; template <int TYPE>
; DI void attn_item(KargPtr p, int b, int h, int qb, unsigned char* smem) {
;     ...
;     auto compute = [&](const int kt, const int buf) __attribute__((always_inline)) {
;         const unsigned char* kb = smem + buf * BUFB; const unsigned char* vb = kb + KBYTES;
;         const int k0 = kt * 64;
;         bool need;
;         if (TYPE == 0) {
;             if (!wdone && k0 <= qw + 31) wdone = (__all(qbound + *(const float*)(vb + VBYTES) - m < -150.f) != 0);
;             need = (k0 <= qw + 31) && !wdone;
.LBB0_620:
	v_mov_b32_e32 v225, s3
	ds_read_b32 v225, v225 offset:20480
	s_add_i32 s12, s74, 0xffffff81
	s_cmp_lt_u32 s84, s78
	s_cselect_b64 s[82:83], -1, 0
	s_and_b64 s[10:11], s[82:83], exec
	s_cselect_b32 s10, s12, 0
	v_add_u32_e32 v0, s10, v173
	v_ashrrev_i32_e32 v1, 31, v0
	v_lshlrev_b64 v[0:1], 10, v[0:1]
	v_lshl_add_u64 v[0:1], s[88:89], 0, v[0:1]
	v_lshl_add_u64 v[0:1], v[0:1], 0, v[156:157]
	global_load_dwordx4 v[4:7], v[0:1], off
	v_add_u32_e32 v0, s10, v174
	v_ashrrev_i32_e32 v1, 31, v0
	s_ashr_i32 s11, s10, 31
	v_lshlrev_b64 v[0:1], 10, v[0:1]
	s_lshl_b64 s[12:13], s[10:11], 7
	v_lshl_add_u64 v[0:1], s[88:89], 0, v[0:1]
	s_add_u32 s12, s75, s12
	v_lshl_add_u64 v[0:1], v[0:1], 0, v[156:157]
	s_addc_u32 s13, s76, s13
	global_load_dwordx4 v[8:11], v[0:1], off
	v_lshl_add_u64 v[0:1], v[132:133], 1, s[12:13]
	v_lshl_add_u64 v[0:1], v[0:1], 0, v[156:157]
	s_lshl_b64 s[10:11], s[10:11], 2
	global_load_dwordx4 v[12:15], v[0:1], off
	v_lshl_add_u64 v[0:1], v[134:135], 1, s[12:13]
	s_add_u32 s10, s77, s10
	v_lshl_add_u64 v[0:1], v[0:1], 0, v[156:157]
	s_addc_u32 s11, s96, s11
	global_load_dwordx4 v[124:127], v[0:1], off
	v_lshl_add_u64 v[0:1], s[10:11], 0, v[158:159]
	global_load_dword v190, v[0:1], off
	v_and_b32_e32 v0, 1, v189
	s_add_i32 s12, s74, 1
	v_cmp_eq_u32_e64 s[10:11], 1, v0
	v_cmp_gt_i32_e32 vcc, s12, v184
	s_xor_b64 s[12:13], s[10:11], -1
	s_nor_b64 s[16:17], s[10:11], vcc
	s_or_b64 s[12:13], s[12:13], vcc
	s_and_saveexec_b64 s[14:15], s[16:17]
	s_cbranch_execz .LBB0_622
	s_mov_b32 s16, 0xc3160000
	s_waitcnt lgkmcnt(0)
	v_add_f32_e32 v0, v182, v225
	v_sub_f32_e32 v0, v0, v160
	v_cmp_gt_f32_e32 vcc, s16, v0
	s_cmp_eq_u64 vcc, exec
	s_cselect_b64 s[16:17], -1, 0
	v_cndmask_b32_e64 v189, 0, 1, s[16:17]
	s_andn2_b64 s[10:11], s[10:11], exec
	s_and_b64 s[16:17], s[16:17], exec
	s_andn2_b64 s[12:13], s[12:13], exec
	s_or_b64 s[10:11], s[10:11], s[16:17]
